# adds: P2 ticket queue: the next ticket's atomic is awaited at the next loop top (wave 0 only) instead of right after issue
# speedup vs baseline: 1.0009x; 1.0009x over previous
.LBB0_411:
	s_waitcnt lgkmcnt(0)
	s_barrier
	s_mov_b64 s[0:1], exec
	v_readlane_b32 s2, v254, 2
	v_readlane_b32 s3, v254, 3
	s_and_b64 s[2:3], s[0:1], s[2:3]
	s_mov_b64 exec, s[2:3]
	v_mov_b32_e32 v3, s15
	s_cbranch_execz .Lq_ticket_ready
	s_waitcnt vmcnt(0)
.Lq_ticket_ready:
	ds_write_b32 v3, v101
	s_or_b64 exec, exec, s[0:1]
	s_waitcnt lgkmcnt(0)
	s_barrier
	ds_read_b32 v3, v103
	s_movk_i32 s0, 0x2ff
	s_waitcnt lgkmcnt(0)
	v_cmp_lt_i32_e64 s[2:3], s0, v3
	v_readfirstlane_b32 s70, v3
	s_and_b64 vcc, exec, s[2:3]
	s_cbranch_vccnz .LBB0_410
	s_mov_b64 s[0:1], exec
	v_readlane_b32 s4, v254, 2
	v_readlane_b32 s5, v254, 3
	s_and_b64 s[4:5], s[0:1], s[4:5]
	s_mov_b64 exec, s[4:5]
	s_cbranch_execz .LBB0_419
	s_mov_b64 s[6:7], exec
	v_mbcnt_lo_u32_b32 v3, s6, 0
	v_mbcnt_hi_u32_b32 v3, s7, v3
	v_cmp_eq_u32_e32 vcc, 0, v3
	s_and_saveexec_b64 s[4:5], vcc
	s_cbranch_execz .LBB0_417
	s_bcnt1_i32_b64 s6, s[6:7]
	v_mov_b32_e32 v4, s6
	global_atomic_add v101, v2, v4, s[74:75] sc0
.LBB0_417:
	s_or_b64 exec, exec, s[4:5]
	s_or_b64 exec, exec, s[0:1]
	s_cmpk_gt_i32 s70, 0x7f
	s_mov_b64 s[0:1], -1
	s_cbranch_scc1 .LBB0_420
